# O1 L1+L3 modes 1/2: quad-coalesced stores via wave-private LDS tile (lane field substitution), on top of v27
# baseline (speedup 1.0000x reference)
; __device__ __forceinline__ unsigned cvt_pk_bf16(float lo, float hi) { unsigned r; asm("v_cvt_pk_bf16_f32 %0, %1, %2" : "=v"(r) : "v"(lo), "v"(hi)); return r; }
; __device__ __forceinline__ float silu_f(float x) { return x * __builtin_amdgcn_rcpf(1.f + __builtin_amdgcn_exp2f(-LOG2E * x)); }
;     __device__ __forceinline__ void operator()(const f32x4 (&acc)[2][2][4][2], const Unit& u, int wr, int wc, int fr, int fq, LAS unsigned char* xs, int wid, int lane) const {
;     ...
;         } else if (mode == 1 || mode == 2) {
; #pragma unroll
;             for (int ai = 0; ai < 2; ++ai)
; #pragma unroll
;                 for (int m = 0; m < 4; ++m) {
;                     const float r = rs[ai][m];
;                     bf16_t* rowp = base + (size_t)(row0 + ai * 128 + m * 16 + fr) * ldc + wc * 32 + 8 * fq;
;                     float o[8];
; #pragma unroll
;                     for (int n = 0; n < 2; ++n)
; #pragma unroll
;                         for (int j = 0; j < 4; ++j) { const float a = acc[ai][0][m][n][j] * r, b = acc[ai][1][m][n][j] * r; o[4 * n + j] = (mode == 1) ? a * b : a * silu_f(b); }
;                     u32x4 w; w.x = cvt_pk_bf16(o[0], o[1]); w.y = cvt_pk_bf16(o[2], o[3]); w.z = cvt_pk_bf16(o[4], o[5]); w.w = cvt_pk_bf16(o[6], o[7]);
;                     *(u32x4*)rowp = w;
.LBB0_741:
	v_and_b32_e32 v186, 63, v254
	v_lshrrev_b32_e32 v180, 2, v186
	v_and_b32_e32 v182, 3, v186
	v_bfe_u32 v185, v186, 4, 2
	v_xor_b32_e32 v185, v182, v185
	v_lshlrev_b32_e32 v185, 4, v185
	v_lshl_add_u32 v185, v180, 6, v185
	v_and_b32_e32 v184, 0x1c0, v254
	v_lshlrev_b32_e32 v184, 6, v184
	v_add_u32_e32 v184, 0x20000, v184
	v_add_u32_e32 v185, v184, v185
	v_and_b32_e32 v186, 15, v186
	v_lshlrev_b32_e32 v186, 6, v186
	v_add_u32_e32 v184, v184, v186
	v_bfe_u32 v186, v254, 4, 2
	v_bfe_u32 v187, v254, 2, 2
	v_xor_b32_e32 v186, v186, v187
	v_lshl_add_u32 v184, v186, 4, v184
	v_or_b32_e32 v180, s68, v180
	v_lshlrev_b32_e32 v182, 4, v182
	v_mov_b32_e32 v183, 0
	s_waitcnt lgkmcnt(7)
	v_mul_f32_e32 v120, v120, v174
	v_mul_f32_e32 v159, 0xbfb8aa3b, v120
	s_add_u32 s0, s70, s89
	v_exp_f32_e32 v159, v159
	s_addc_u32 s1, s71, 0
	v_mov_b32_e32 v151, v137
	v_lshl_add_u64 v[176:177], s[0:1], 0, v[182:183]
	s_ashr_i32 s0, s68, 31
	v_mul_lo_u32 v151, s65, v180
	s_mul_i32 s0, s64, s0
	v_mad_u64_u32 v[178:179], s[18:19], s64, v180, 0
	v_add3_u32 v179, v179, s0, v151
	v_add_f32_e32 v151, 1.0, v159
	v_rcp_f32_e32 v151, v151
	v_mul_f32_e32 v121, v121, v174
	v_mul_f32_e32 v159, 0xbfb8aa3b, v121
	v_exp_f32_e32 v159, v159
	v_mul_f32_e32 v151, v120, v151
	v_mul_f32_e32 v124, v124, v174
	v_cndmask_b32_e64 v120, v151, v120, s[12:13]
	v_mul_f32_e32 v120, v124, v120
	v_add_f32_e32 v124, 1.0, v159
	v_mul_f32_e32 v122, v122, v174
	v_rcp_f32_e32 v124, v124
	v_mul_f32_e32 v151, 0xbfb8aa3b, v122
	v_exp_f32_e32 v151, v151
	v_mul_f32_e32 v123, v123, v174
	v_mul_f32_e32 v124, v121, v124
	v_cndmask_b32_e64 v121, v124, v121, s[12:13]
	v_add_f32_e32 v124, 1.0, v151
	v_mul_f32_e32 v151, 0xbfb8aa3b, v123
	v_exp_f32_e32 v151, v151
	v_mul_f32_e32 v125, v125, v174
	v_rcp_f32_e32 v124, v124
	v_mul_f32_e32 v121, v125, v121
	v_mul_f32_e32 v125, v126, v174
	v_add_f32_e32 v126, 1.0, v151
	v_rcp_f32_e32 v126, v126
	v_mul_f32_e32 v124, v122, v124
	v_cndmask_b32_e64 v122, v124, v122, s[12:13]
	v_mul_f32_e32 v112, v112, v174
	v_mul_f32_e32 v122, v125, v122
	v_mul_f32_e32 v125, v123, v126
	v_mul_f32_e32 v126, 0xbfb8aa3b, v112
	v_exp_f32_e32 v126, v126
	v_mul_f32_e32 v124, v127, v174
	v_cndmask_b32_e64 v123, v125, v123, s[12:13]
	v_mul_f32_e32 v123, v124, v123
	v_add_f32_e32 v124, 1.0, v126
	v_rcp_f32_e32 v124, v124
	v_mul_f32_e32 v113, v113, v174
	v_mul_f32_e32 v125, 0xbfb8aa3b, v113
	v_exp_f32_e32 v125, v125
	v_mul_f32_e32 v124, v112, v124
	v_mul_f32_e32 v116, v116, v174
	v_cndmask_b32_e64 v112, v124, v112, s[12:13]
	v_mul_f32_e32 v124, v116, v112
	v_add_f32_e32 v112, 1.0, v125
	v_mul_f32_e32 v114, v114, v174
	v_rcp_f32_e32 v112, v112
	v_mul_f32_e32 v116, 0xbfb8aa3b, v114
	v_exp_f32_e32 v116, v116
	v_mul_f32_e32 v115, v115, v174
	v_mul_f32_e32 v112, v113, v112
	v_cndmask_b32_e64 v112, v112, v113, s[12:13]
	v_add_f32_e32 v113, 1.0, v116
	v_mul_f32_e32 v116, 0xbfb8aa3b, v115
	v_exp_f32_e32 v116, v116
	v_rcp_f32_e32 v113, v113
	v_mul_f32_e32 v117, v117, v174
	v_mul_f32_e32 v125, v117, v112
	v_add_f32_e32 v116, 1.0, v116
	v_rcp_f32_e32 v116, v116
	v_mul_f32_e32 v113, v114, v113
	v_mul_f32_e32 v112, v118, v174
	v_cndmask_b32_e64 v113, v113, v114, s[12:13]
	v_mul_f32_e32 v118, v112, v113
	v_mul_f32_e32 v113, v115, v116
	v_mul_f32_e32 v112, v119, v174
	v_cndmask_b32_e64 v113, v113, v115, s[12:13]
	v_mul_f32_e32 v115, v112, v113
	v_lshl_add_u64 v[116:117], v[178:179], 1, v[176:177]
	v_cvt_pk_bf16_f32 v112, v120, v121
	v_cvt_pk_bf16_f32 v113, v122, v123
	v_cvt_pk_bf16_f32 v114, v124, v125
	v_cvt_pk_bf16_f32 v115, v118, v115
	ds_write_b128 v184, v[112:115]
	ds_read_b128 v[188:191], v185
	v_mov_b32_e32 v196, v116
	v_mov_b32_e32 v197, v117
	s_waitcnt lgkmcnt(6)
	v_mul_f32_e32 v104, v104, v172
	v_mul_f32_e32 v113, 0xbfb8aa3b, v104
	v_exp_f32_e32 v115, v113
	v_or_b32_e32 v112, 16, v180
	v_mul_lo_u32 v114, s65, v112
	v_mad_u64_u32 v[112:113], s[18:19], s64, v112, 0
	v_add3_u32 v113, v113, s0, v114
	v_add_f32_e32 v114, 1.0, v115
	v_rcp_f32_e32 v114, v114
	v_mul_f32_e32 v105, v105, v172
	v_mul_f32_e32 v115, 0xbfb8aa3b, v105
	v_exp_f32_e32 v115, v115
	v_mul_f32_e32 v114, v104, v114
	v_mul_f32_e32 v108, v108, v172
	v_cndmask_b32_e64 v104, v114, v104, s[12:13]
	v_mul_f32_e32 v104, v108, v104
	v_add_f32_e32 v108, 1.0, v115
	v_mul_f32_e32 v106, v106, v172
	v_rcp_f32_e32 v108, v108
	v_mul_f32_e32 v114, 0xbfb8aa3b, v106
	v_exp_f32_e32 v114, v114
	v_mul_f32_e32 v107, v107, v172
	v_mul_f32_e32 v108, v105, v108
	v_cndmask_b32_e64 v105, v108, v105, s[12:13]
	v_add_f32_e32 v108, 1.0, v114
	v_mul_f32_e32 v114, 0xbfb8aa3b, v107
	v_exp_f32_e32 v114, v114
	v_mul_f32_e32 v109, v109, v172
	v_rcp_f32_e32 v108, v108
	v_mul_f32_e32 v105, v109, v105
	v_mul_f32_e32 v109, v110, v172
	v_add_f32_e32 v110, 1.0, v114
	v_rcp_f32_e32 v110, v110
	v_mul_f32_e32 v108, v106, v108
	v_cndmask_b32_e64 v106, v108, v106, s[12:13]
	v_mul_f32_e32 v96, v96, v172
	v_mul_f32_e32 v106, v109, v106
	v_mul_f32_e32 v109, v107, v110
	v_mul_f32_e32 v110, 0xbfb8aa3b, v96
	v_exp_f32_e32 v110, v110
	v_mul_f32_e32 v108, v111, v172
	v_cndmask_b32_e64 v107, v109, v107, s[12:13]
	v_mul_f32_e32 v107, v108, v107
	v_add_f32_e32 v108, 1.0, v110
	v_rcp_f32_e32 v108, v108
	v_mul_f32_e32 v97, v97, v172
	v_mul_f32_e32 v109, 0xbfb8aa3b, v97
	v_exp_f32_e32 v109, v109
	v_mul_f32_e32 v108, v96, v108
	v_mul_f32_e32 v100, v100, v172
	v_cndmask_b32_e64 v96, v108, v96, s[12:13]
	v_mul_f32_e32 v108, v100, v96
	v_add_f32_e32 v96, 1.0, v109
	v_mul_f32_e32 v98, v98, v172
	v_rcp_f32_e32 v96, v96
	v_mul_f32_e32 v100, 0xbfb8aa3b, v98
	v_exp_f32_e32 v100, v100
	v_mul_f32_e32 v99, v99, v172
	v_mul_f32_e32 v96, v97, v96
	v_cndmask_b32_e64 v96, v96, v97, s[12:13]
	v_add_f32_e32 v97, 1.0, v100
	v_mul_f32_e32 v100, 0xbfb8aa3b, v99
	v_exp_f32_e32 v100, v100
	v_rcp_f32_e32 v97, v97
	v_mul_f32_e32 v101, v101, v172
	v_mul_f32_e32 v109, v101, v96
	v_add_f32_e32 v100, 1.0, v100
	v_rcp_f32_e32 v100, v100
	v_mul_f32_e32 v97, v98, v97
	v_mul_f32_e32 v96, v102, v172
	v_cndmask_b32_e64 v97, v97, v98, s[12:13]
	v_mul_f32_e32 v102, v96, v97
	v_mul_f32_e32 v97, v99, v100
	v_mul_f32_e32 v96, v103, v172
	v_cndmask_b32_e64 v97, v97, v99, s[12:13]
	v_mul_f32_e32 v99, v96, v97
	v_lshl_add_u64 v[100:101], v[112:113], 1, v[176:177]
	v_cvt_pk_bf16_f32 v96, v104, v105
	v_cvt_pk_bf16_f32 v97, v106, v107
	v_cvt_pk_bf16_f32 v98, v108, v109
	v_cvt_pk_bf16_f32 v99, v102, v99
	ds_write_b128 v184, v[96:99] offset:1024
	ds_read_b128 v[192:195], v185 offset:1024
	v_mov_b32_e32 v198, v100
	v_mov_b32_e32 v199, v101
	s_waitcnt lgkmcnt(2)
; __device__ __forceinline__ unsigned cvt_pk_bf16(float lo, float hi) { unsigned r; asm("v_cvt_pk_bf16_f32 %0, %1, %2" : "=v"(r) : "v"(lo), "v"(hi)); return r; }
; __device__ __forceinline__ float silu_f(float x) { return x * __builtin_amdgcn_rcpf(1.f + __builtin_amdgcn_exp2f(-LOG2E * x)); }
;     __device__ __forceinline__ void operator()(const f32x4 (&acc)[2][2][4][2], const Unit& u, int wr, int wc, int fr, int fq, LAS unsigned char* xs, int wid, int lane) const {
;     ...
;                 for (int m = 0; m < 4; ++m) {
;                     const float r = rs[ai][m];
;                     bf16_t* rowp = base + (size_t)(row0 + ai * 128 + m * 16 + fr) * ldc + wc * 32 + 8 * fq;
;                     float o[8];
; #pragma unroll
;                     for (int n = 0; n < 2; ++n)
; #pragma unroll
;                         for (int j = 0; j < 4; ++j) { const float a = acc[ai][0][m][n][j] * r, b = acc[ai][1][m][n][j] * r; o[4 * n + j] = (mode == 1) ? a * b : a * silu_f(b); }
;                     u32x4 w; w.x = cvt_pk_bf16(o[0], o[1]); w.y = cvt_pk_bf16(o[2], o[3]); w.z = cvt_pk_bf16(o[4], o[5]); w.w = cvt_pk_bf16(o[6], o[7]);
;                     *(u32x4*)rowp = w;
	global_store_dwordx4 v[196:197], v[188:191], off
	s_waitcnt lgkmcnt(5)
	v_mul_f32_e32 v88, v88, v170
	v_mul_f32_e32 v97, 0xbfb8aa3b, v88
	v_exp_f32_e32 v99, v97
	v_or_b32_e32 v96, 32, v180
	v_mul_lo_u32 v98, s65, v96
	v_mad_u64_u32 v[96:97], s[18:19], s64, v96, 0
	v_add3_u32 v97, v97, s0, v98
	v_add_f32_e32 v98, 1.0, v99
	v_rcp_f32_e32 v98, v98
	v_mul_f32_e32 v89, v89, v170
	v_mul_f32_e32 v99, 0xbfb8aa3b, v89
	v_exp_f32_e32 v99, v99
	v_mul_f32_e32 v98, v88, v98
	v_mul_f32_e32 v92, v92, v170
	v_cndmask_b32_e64 v88, v98, v88, s[12:13]
	v_mul_f32_e32 v88, v92, v88
	v_add_f32_e32 v92, 1.0, v99
	v_mul_f32_e32 v90, v90, v170
	v_rcp_f32_e32 v92, v92
	v_mul_f32_e32 v98, 0xbfb8aa3b, v90
	v_exp_f32_e32 v98, v98
	v_mul_f32_e32 v91, v91, v170
	v_mul_f32_e32 v92, v89, v92
	v_cndmask_b32_e64 v89, v92, v89, s[12:13]
	v_add_f32_e32 v92, 1.0, v98
	v_mul_f32_e32 v98, 0xbfb8aa3b, v91
	v_exp_f32_e32 v98, v98
	v_mul_f32_e32 v93, v93, v170
	v_rcp_f32_e32 v92, v92
	v_mul_f32_e32 v89, v93, v89
	v_mul_f32_e32 v93, v94, v170
	v_add_f32_e32 v94, 1.0, v98
	v_rcp_f32_e32 v94, v94
	v_mul_f32_e32 v92, v90, v92
	v_cndmask_b32_e64 v90, v92, v90, s[12:13]
	v_mul_f32_e32 v80, v80, v170
	v_mul_f32_e32 v90, v93, v90
	v_mul_f32_e32 v93, v91, v94
	v_mul_f32_e32 v94, 0xbfb8aa3b, v80
	v_exp_f32_e32 v94, v94
	v_mul_f32_e32 v92, v95, v170
	v_cndmask_b32_e64 v91, v93, v91, s[12:13]
	v_mul_f32_e32 v91, v92, v91
	v_add_f32_e32 v92, 1.0, v94
	v_rcp_f32_e32 v92, v92
	v_mul_f32_e32 v81, v81, v170
	v_mul_f32_e32 v93, 0xbfb8aa3b, v81
	v_exp_f32_e32 v93, v93
	v_mul_f32_e32 v92, v80, v92
	v_mul_f32_e32 v84, v84, v170
	v_cndmask_b32_e64 v80, v92, v80, s[12:13]
	v_mul_f32_e32 v92, v84, v80
	v_add_f32_e32 v80, 1.0, v93
	v_mul_f32_e32 v82, v82, v170
	v_rcp_f32_e32 v80, v80
	v_mul_f32_e32 v84, 0xbfb8aa3b, v82
	v_exp_f32_e32 v84, v84
	v_mul_f32_e32 v83, v83, v170
	v_mul_f32_e32 v80, v81, v80
	v_cndmask_b32_e64 v80, v80, v81, s[12:13]
	v_add_f32_e32 v81, 1.0, v84
	v_mul_f32_e32 v84, 0xbfb8aa3b, v83
	v_exp_f32_e32 v84, v84
	v_rcp_f32_e32 v81, v81
	v_mul_f32_e32 v85, v85, v170
	v_mul_f32_e32 v93, v85, v80
	v_add_f32_e32 v84, 1.0, v84
	v_rcp_f32_e32 v84, v84
	v_mul_f32_e32 v81, v82, v81
	v_mul_f32_e32 v80, v86, v170
	v_cndmask_b32_e64 v81, v81, v82, s[12:13]
	v_mul_f32_e32 v86, v80, v81
	v_mul_f32_e32 v81, v83, v84
	v_mul_f32_e32 v80, v87, v170
	v_cndmask_b32_e64 v81, v81, v83, s[12:13]
	v_mul_f32_e32 v83, v80, v81
	v_lshl_add_u64 v[84:85], v[96:97], 1, v[176:177]
	v_cvt_pk_bf16_f32 v80, v88, v89
	v_cvt_pk_bf16_f32 v81, v90, v91
	v_cvt_pk_bf16_f32 v82, v92, v93
	v_cvt_pk_bf16_f32 v83, v86, v83
	ds_write_b128 v184, v[80:83]
	ds_read_b128 v[188:191], v185
	v_mov_b32_e32 v196, v84
	v_mov_b32_e32 v197, v85
	s_waitcnt lgkmcnt(2)
	global_store_dwordx4 v[198:199], v[192:195], off
	s_waitcnt lgkmcnt(4)
	v_mul_f32_e32 v72, v72, v168
	v_mul_f32_e32 v81, 0xbfb8aa3b, v72
	v_exp_f32_e32 v83, v81
	v_or_b32_e32 v80, 48, v180
	v_mul_lo_u32 v82, s65, v80
	v_mad_u64_u32 v[80:81], s[18:19], s64, v80, 0
	v_add3_u32 v81, v81, s0, v82
	v_add_f32_e32 v82, 1.0, v83
	v_rcp_f32_e32 v82, v82
	v_mul_f32_e32 v73, v73, v168
	v_mul_f32_e32 v83, 0xbfb8aa3b, v73
	v_exp_f32_e32 v83, v83
	v_mul_f32_e32 v82, v72, v82
	v_mul_f32_e32 v76, v76, v168
	v_cndmask_b32_e64 v72, v82, v72, s[12:13]
	v_mul_f32_e32 v72, v76, v72
	v_add_f32_e32 v76, 1.0, v83
	v_mul_f32_e32 v74, v74, v168
	v_rcp_f32_e32 v76, v76
	v_mul_f32_e32 v82, 0xbfb8aa3b, v74
	v_exp_f32_e32 v82, v82
	v_mul_f32_e32 v75, v75, v168
	v_mul_f32_e32 v76, v73, v76
	v_cndmask_b32_e64 v73, v76, v73, s[12:13]
	v_add_f32_e32 v76, 1.0, v82
	v_mul_f32_e32 v82, 0xbfb8aa3b, v75
	v_exp_f32_e32 v82, v82
	v_mul_f32_e32 v77, v77, v168
	v_rcp_f32_e32 v76, v76
	v_mul_f32_e32 v73, v77, v73
	v_mul_f32_e32 v77, v78, v168
	v_add_f32_e32 v78, 1.0, v82
	v_rcp_f32_e32 v78, v78
	v_mul_f32_e32 v76, v74, v76
	v_cndmask_b32_e64 v74, v76, v74, s[12:13]
	v_mul_f32_e32 v64, v64, v168
	v_mul_f32_e32 v74, v77, v74
	v_mul_f32_e32 v77, v75, v78
	v_mul_f32_e32 v78, 0xbfb8aa3b, v64
	v_exp_f32_e32 v78, v78
	v_mul_f32_e32 v76, v79, v168
	v_cndmask_b32_e64 v75, v77, v75, s[12:13]
	v_mul_f32_e32 v75, v76, v75
	v_add_f32_e32 v76, 1.0, v78
	v_rcp_f32_e32 v76, v76
	v_mul_f32_e32 v65, v65, v168
	v_mul_f32_e32 v77, 0xbfb8aa3b, v65
	v_exp_f32_e32 v77, v77
	v_mul_f32_e32 v76, v64, v76
	v_mul_f32_e32 v68, v68, v168
	v_cndmask_b32_e64 v64, v76, v64, s[12:13]
	v_mul_f32_e32 v76, v68, v64
	v_add_f32_e32 v64, 1.0, v77
	v_mul_f32_e32 v66, v66, v168
	v_rcp_f32_e32 v64, v64
	v_mul_f32_e32 v68, 0xbfb8aa3b, v66
	v_exp_f32_e32 v68, v68
	v_mul_f32_e32 v67, v67, v168
	v_mul_f32_e32 v64, v65, v64
	v_cndmask_b32_e64 v64, v64, v65, s[12:13]
	v_add_f32_e32 v65, 1.0, v68
	v_mul_f32_e32 v68, 0xbfb8aa3b, v67
	v_exp_f32_e32 v68, v68
	v_rcp_f32_e32 v65, v65
	v_mul_f32_e32 v69, v69, v168
	v_mul_f32_e32 v77, v69, v64
	v_add_f32_e32 v68, 1.0, v68
	v_rcp_f32_e32 v68, v68
	v_mul_f32_e32 v65, v66, v65
	v_mul_f32_e32 v64, v70, v168
	v_cndmask_b32_e64 v65, v65, v66, s[12:13]
	v_mul_f32_e32 v70, v64, v65
	v_mul_f32_e32 v65, v67, v68
	v_mul_f32_e32 v64, v71, v168
	v_cndmask_b32_e64 v65, v65, v67, s[12:13]
	v_mul_f32_e32 v67, v64, v65
	v_lshl_add_u64 v[68:69], v[80:81], 1, v[176:177]
	v_cvt_pk_bf16_f32 v64, v72, v73
	v_cvt_pk_bf16_f32 v65, v74, v75
	v_cvt_pk_bf16_f32 v66, v76, v77
	v_cvt_pk_bf16_f32 v67, v70, v67
	ds_write_b128 v184, v[64:67] offset:1024
	ds_read_b128 v[192:195], v185 offset:1024
	v_mov_b32_e32 v198, v68
	v_mov_b32_e32 v199, v69
	s_waitcnt lgkmcnt(2)
	global_store_dwordx4 v[196:197], v[188:191], off
	s_nop 1
	v_add_u32_e32 v64, 0x80, v180
	v_ashrrev_i32_e32 v65, 31, v64
	s_waitcnt lgkmcnt(3)
; __device__ __forceinline__ unsigned cvt_pk_bf16(float lo, float hi) { unsigned r; asm("v_cvt_pk_bf16_f32 %0, %1, %2" : "=v"(r) : "v"(lo), "v"(hi)); return r; }
; __device__ __forceinline__ float silu_f(float x) { return x * __builtin_amdgcn_rcpf(1.f + __builtin_amdgcn_exp2f(-LOG2E * x)); }
;     __device__ __forceinline__ void operator()(const f32x4 (&acc)[2][2][4][2], const Unit& u, int wr, int wc, int fr, int fq, LAS unsigned char* xs, int wid, int lane) const {
;     ...
;                 for (int m = 0; m < 4; ++m) {
;                     const float r = rs[ai][m];
;                     bf16_t* rowp = base + (size_t)(row0 + ai * 128 + m * 16 + fr) * ldc + wc * 32 + 8 * fq;
;                     float o[8];
; #pragma unroll
;                     for (int n = 0; n < 2; ++n)
; #pragma unroll
;                         for (int j = 0; j < 4; ++j) { const float a = acc[ai][0][m][n][j] * r, b = acc[ai][1][m][n][j] * r; o[4 * n + j] = (mode == 1) ? a * b : a * silu_f(b); }
;                     u32x4 w; w.x = cvt_pk_bf16(o[0], o[1]); w.y = cvt_pk_bf16(o[2], o[3]); w.z = cvt_pk_bf16(o[4], o[5]); w.w = cvt_pk_bf16(o[6], o[7]);
;                     *(u32x4*)rowp = w;
	v_mul_f32_e32 v56, v56, v166
	v_mul_lo_u32 v66, s64, v65
	v_mul_f32_e32 v65, 0xbfb8aa3b, v56
	v_exp_f32_e32 v68, v65
	v_mul_lo_u32 v67, s65, v64
	v_mad_u64_u32 v[64:65], s[0:1], s64, v64, 0
	v_add3_u32 v65, v65, v66, v67
	v_add_f32_e32 v66, 1.0, v68
	v_rcp_f32_e32 v66, v66
	v_mul_f32_e32 v57, v57, v166
	v_mul_f32_e32 v67, 0xbfb8aa3b, v57
	v_exp_f32_e32 v67, v67
	v_mul_f32_e32 v66, v56, v66
	v_mul_f32_e32 v60, v60, v166
	v_cndmask_b32_e64 v56, v66, v56, s[12:13]
	v_mul_f32_e32 v56, v60, v56
	v_add_f32_e32 v60, 1.0, v67
	v_mul_f32_e32 v58, v58, v166
	v_rcp_f32_e32 v60, v60
	v_mul_f32_e32 v66, 0xbfb8aa3b, v58
	v_exp_f32_e32 v66, v66
	v_mul_f32_e32 v59, v59, v166
	v_mul_f32_e32 v60, v57, v60
	v_cndmask_b32_e64 v57, v60, v57, s[12:13]
	v_add_f32_e32 v60, 1.0, v66
	v_mul_f32_e32 v66, 0xbfb8aa3b, v59
	v_exp_f32_e32 v66, v66
	v_mul_f32_e32 v61, v61, v166
	v_rcp_f32_e32 v60, v60
	v_mul_f32_e32 v57, v61, v57
	v_mul_f32_e32 v61, v62, v166
	v_add_f32_e32 v62, 1.0, v66
	v_rcp_f32_e32 v62, v62
	v_mul_f32_e32 v60, v58, v60
	v_cndmask_b32_e64 v58, v60, v58, s[12:13]
	v_mul_f32_e32 v48, v48, v166
	v_mul_f32_e32 v58, v61, v58
	v_mul_f32_e32 v61, v59, v62
	v_mul_f32_e32 v62, 0xbfb8aa3b, v48
	v_exp_f32_e32 v62, v62
	v_mul_f32_e32 v60, v63, v166
	v_cndmask_b32_e64 v59, v61, v59, s[12:13]
	v_mul_f32_e32 v59, v60, v59
	v_add_f32_e32 v60, 1.0, v62
	v_rcp_f32_e32 v60, v60
	v_mul_f32_e32 v49, v49, v166
	v_mul_f32_e32 v61, 0xbfb8aa3b, v49
	v_exp_f32_e32 v61, v61
	v_mul_f32_e32 v60, v48, v60
	v_mul_f32_e32 v52, v52, v166
	v_cndmask_b32_e64 v48, v60, v48, s[12:13]
	v_mul_f32_e32 v60, v52, v48
	v_add_f32_e32 v48, 1.0, v61
	v_mul_f32_e32 v50, v50, v166
	v_rcp_f32_e32 v48, v48
	v_mul_f32_e32 v52, 0xbfb8aa3b, v50
	v_exp_f32_e32 v52, v52
	v_mul_f32_e32 v51, v51, v166
	v_mul_f32_e32 v48, v49, v48
	v_cndmask_b32_e64 v48, v48, v49, s[12:13]
	v_add_f32_e32 v49, 1.0, v52
	v_mul_f32_e32 v52, 0xbfb8aa3b, v51
	v_exp_f32_e32 v52, v52
	v_rcp_f32_e32 v49, v49
	v_mul_f32_e32 v53, v53, v166
	v_mul_f32_e32 v61, v53, v48
	v_add_f32_e32 v52, 1.0, v52
	v_rcp_f32_e32 v52, v52
	v_mul_f32_e32 v49, v50, v49
	v_mul_f32_e32 v48, v54, v166
	v_cndmask_b32_e64 v49, v49, v50, s[12:13]
	v_mul_f32_e32 v54, v48, v49
	v_mul_f32_e32 v49, v51, v52
	v_mul_f32_e32 v48, v55, v166
	v_cndmask_b32_e64 v49, v49, v51, s[12:13]
	v_mul_f32_e32 v51, v48, v49
	v_lshl_add_u64 v[52:53], v[64:65], 1, v[176:177]
	v_cvt_pk_bf16_f32 v48, v56, v57
	v_cvt_pk_bf16_f32 v49, v58, v59
	v_cvt_pk_bf16_f32 v50, v60, v61
	v_cvt_pk_bf16_f32 v51, v54, v51
	ds_write_b128 v184, v[48:51]
	ds_read_b128 v[188:191], v185
	v_mov_b32_e32 v196, v52
	v_mov_b32_e32 v197, v53
	s_waitcnt lgkmcnt(2)
	global_store_dwordx4 v[198:199], v[192:195], off
	s_nop 1
	v_add_u32_e32 v48, 0x90, v180
	v_ashrrev_i32_e32 v49, 31, v48
	s_waitcnt lgkmcnt(2)
	v_mul_f32_e32 v40, v40, v164
	v_mul_lo_u32 v50, s64, v49
	v_mul_f32_e32 v49, 0xbfb8aa3b, v40
	v_exp_f32_e32 v52, v49
	v_mul_lo_u32 v51, s65, v48
	v_mad_u64_u32 v[48:49], s[0:1], s64, v48, 0
	v_add3_u32 v49, v49, v50, v51
	v_add_f32_e32 v50, 1.0, v52
	v_rcp_f32_e32 v50, v50
	v_mul_f32_e32 v41, v41, v164
	v_mul_f32_e32 v51, 0xbfb8aa3b, v41
	v_exp_f32_e32 v51, v51
	v_mul_f32_e32 v50, v40, v50
	v_mul_f32_e32 v44, v44, v164
	v_cndmask_b32_e64 v40, v50, v40, s[12:13]
	v_mul_f32_e32 v40, v44, v40
	v_add_f32_e32 v44, 1.0, v51
	v_mul_f32_e32 v42, v42, v164
	v_rcp_f32_e32 v44, v44
	v_mul_f32_e32 v50, 0xbfb8aa3b, v42
	v_exp_f32_e32 v50, v50
	v_mul_f32_e32 v43, v43, v164
	v_mul_f32_e32 v44, v41, v44
	v_cndmask_b32_e64 v41, v44, v41, s[12:13]
	v_add_f32_e32 v44, 1.0, v50
	v_mul_f32_e32 v50, 0xbfb8aa3b, v43
	v_exp_f32_e32 v50, v50
	v_mul_f32_e32 v45, v45, v164
	v_rcp_f32_e32 v44, v44
	v_mul_f32_e32 v41, v45, v41
	v_mul_f32_e32 v45, v46, v164
	v_add_f32_e32 v46, 1.0, v50
	v_rcp_f32_e32 v46, v46
	v_mul_f32_e32 v44, v42, v44
	v_cndmask_b32_e64 v42, v44, v42, s[12:13]
	v_mul_f32_e32 v32, v32, v164
	v_mul_f32_e32 v42, v45, v42
	v_mul_f32_e32 v45, v43, v46
	v_mul_f32_e32 v46, 0xbfb8aa3b, v32
	v_exp_f32_e32 v46, v46
	v_mul_f32_e32 v44, v47, v164
	v_cndmask_b32_e64 v43, v45, v43, s[12:13]
	v_mul_f32_e32 v43, v44, v43
	v_add_f32_e32 v44, 1.0, v46
	v_rcp_f32_e32 v44, v44
	v_mul_f32_e32 v33, v33, v164
	v_mul_f32_e32 v45, 0xbfb8aa3b, v33
	v_exp_f32_e32 v45, v45
	v_mul_f32_e32 v44, v32, v44
	v_mul_f32_e32 v36, v36, v164
	v_cndmask_b32_e64 v32, v44, v32, s[12:13]
	v_mul_f32_e32 v44, v36, v32
	v_add_f32_e32 v32, 1.0, v45
	v_mul_f32_e32 v34, v34, v164
	v_rcp_f32_e32 v32, v32
	v_mul_f32_e32 v36, 0xbfb8aa3b, v34
	v_exp_f32_e32 v36, v36
	v_mul_f32_e32 v35, v35, v164
	v_mul_f32_e32 v32, v33, v32
	v_cndmask_b32_e64 v32, v32, v33, s[12:13]
	v_add_f32_e32 v33, 1.0, v36
	v_mul_f32_e32 v36, 0xbfb8aa3b, v35
	v_exp_f32_e32 v36, v36
	v_rcp_f32_e32 v33, v33
	v_mul_f32_e32 v37, v37, v164
	v_mul_f32_e32 v45, v37, v32
	v_add_f32_e32 v36, 1.0, v36
	v_rcp_f32_e32 v36, v36
	v_mul_f32_e32 v33, v34, v33
	v_mul_f32_e32 v32, v38, v164
	v_cndmask_b32_e64 v33, v33, v34, s[12:13]
	v_mul_f32_e32 v38, v32, v33
	v_mul_f32_e32 v33, v35, v36
	v_mul_f32_e32 v32, v39, v164
	v_cndmask_b32_e64 v33, v33, v35, s[12:13]
	v_mul_f32_e32 v35, v32, v33
	v_lshl_add_u64 v[36:37], v[48:49], 1, v[176:177]
	v_cvt_pk_bf16_f32 v32, v40, v41
	v_cvt_pk_bf16_f32 v33, v42, v43
	v_cvt_pk_bf16_f32 v34, v44, v45
	v_cvt_pk_bf16_f32 v35, v38, v35
	ds_write_b128 v184, v[32:35] offset:1024
	ds_read_b128 v[192:195], v185 offset:1024
	v_mov_b32_e32 v198, v36
	v_mov_b32_e32 v199, v37
	s_waitcnt lgkmcnt(2)
	global_store_dwordx4 v[196:197], v[188:191], off
	s_nop 1
	v_add_u32_e32 v32, 0xa0, v180
	v_ashrrev_i32_e32 v33, 31, v32
	s_waitcnt lgkmcnt(1)
; __device__ __forceinline__ unsigned cvt_pk_bf16(float lo, float hi) { unsigned r; asm("v_cvt_pk_bf16_f32 %0, %1, %2" : "=v"(r) : "v"(lo), "v"(hi)); return r; }
; __device__ __forceinline__ float silu_f(float x) { return x * __builtin_amdgcn_rcpf(1.f + __builtin_amdgcn_exp2f(-LOG2E * x)); }
;     __device__ __forceinline__ void operator()(const f32x4 (&acc)[2][2][4][2], const Unit& u, int wr, int wc, int fr, int fq, LAS unsigned char* xs, int wid, int lane) const {
;     ...
;                 for (int m = 0; m < 4; ++m) {
;                     const float r = rs[ai][m];
;                     bf16_t* rowp = base + (size_t)(row0 + ai * 128 + m * 16 + fr) * ldc + wc * 32 + 8 * fq;
;                     float o[8];
; #pragma unroll
;                     for (int n = 0; n < 2; ++n)
; #pragma unroll
;                         for (int j = 0; j < 4; ++j) { const float a = acc[ai][0][m][n][j] * r, b = acc[ai][1][m][n][j] * r; o[4 * n + j] = (mode == 1) ? a * b : a * silu_f(b); }
;                     u32x4 w; w.x = cvt_pk_bf16(o[0], o[1]); w.y = cvt_pk_bf16(o[2], o[3]); w.z = cvt_pk_bf16(o[4], o[5]); w.w = cvt_pk_bf16(o[6], o[7]);
;                     *(u32x4*)rowp = w;
;                     __builtin_amdgcn_sched_barrier(0);
;                 }
	v_mul_f32_e32 v24, v24, v160
	v_mul_lo_u32 v34, s64, v33
	v_mul_f32_e32 v33, 0xbfb8aa3b, v24
	v_exp_f32_e32 v36, v33
	v_mul_lo_u32 v35, s65, v32
	v_mad_u64_u32 v[32:33], s[0:1], s64, v32, 0
	v_add3_u32 v33, v33, v34, v35
	v_add_f32_e32 v34, 1.0, v36
	v_rcp_f32_e32 v34, v34
	v_mul_f32_e32 v25, v25, v160
	v_mul_f32_e32 v35, 0xbfb8aa3b, v25
	v_exp_f32_e32 v35, v35
	v_mul_f32_e32 v34, v24, v34
	v_mul_f32_e32 v28, v28, v160
	v_cndmask_b32_e64 v24, v34, v24, s[12:13]
	v_mul_f32_e32 v24, v28, v24
	v_add_f32_e32 v28, 1.0, v35
	v_mul_f32_e32 v26, v26, v160
	v_rcp_f32_e32 v28, v28
	v_mul_f32_e32 v34, 0xbfb8aa3b, v26
	v_exp_f32_e32 v34, v34
	v_mul_f32_e32 v27, v27, v160
	v_mul_f32_e32 v28, v25, v28
	v_cndmask_b32_e64 v25, v28, v25, s[12:13]
	v_add_f32_e32 v28, 1.0, v34
	v_mul_f32_e32 v34, 0xbfb8aa3b, v27
	v_exp_f32_e32 v34, v34
	v_mul_f32_e32 v29, v29, v160
	v_rcp_f32_e32 v28, v28
	v_mul_f32_e32 v25, v29, v25
	v_mul_f32_e32 v29, v30, v160
	v_add_f32_e32 v30, 1.0, v34
	v_rcp_f32_e32 v30, v30
	v_mul_f32_e32 v28, v26, v28
	v_cndmask_b32_e64 v26, v28, v26, s[12:13]
	v_mul_f32_e32 v16, v16, v160
	v_mul_f32_e32 v26, v29, v26
	v_mul_f32_e32 v29, v27, v30
	v_mul_f32_e32 v30, 0xbfb8aa3b, v16
	v_exp_f32_e32 v30, v30
	v_mul_f32_e32 v28, v31, v160
	v_cndmask_b32_e64 v27, v29, v27, s[12:13]
	v_mul_f32_e32 v27, v28, v27
	v_add_f32_e32 v28, 1.0, v30
	v_rcp_f32_e32 v28, v28
	v_mul_f32_e32 v17, v17, v160
	v_mul_f32_e32 v29, 0xbfb8aa3b, v17
	v_exp_f32_e32 v29, v29
	v_mul_f32_e32 v28, v16, v28
	v_mul_f32_e32 v20, v20, v160
	v_cndmask_b32_e64 v16, v28, v16, s[12:13]
	v_mul_f32_e32 v28, v20, v16
	v_add_f32_e32 v16, 1.0, v29
	v_mul_f32_e32 v18, v18, v160
	v_rcp_f32_e32 v16, v16
	v_mul_f32_e32 v20, 0xbfb8aa3b, v18
	v_exp_f32_e32 v20, v20
	v_mul_f32_e32 v19, v19, v160
	v_mul_f32_e32 v16, v17, v16
	v_cndmask_b32_e64 v16, v16, v17, s[12:13]
	v_add_f32_e32 v17, 1.0, v20
	v_mul_f32_e32 v20, 0xbfb8aa3b, v19
	v_exp_f32_e32 v20, v20
	v_rcp_f32_e32 v17, v17
	v_mul_f32_e32 v21, v21, v160
	v_mul_f32_e32 v29, v21, v16
	v_add_f32_e32 v20, 1.0, v20
	v_rcp_f32_e32 v20, v20
	v_mul_f32_e32 v17, v18, v17
	v_mul_f32_e32 v16, v22, v160
	v_cndmask_b32_e64 v17, v17, v18, s[12:13]
	v_mul_f32_e32 v22, v16, v17
	v_mul_f32_e32 v17, v19, v20
	v_mul_f32_e32 v16, v23, v160
	v_cndmask_b32_e64 v17, v17, v19, s[12:13]
	v_mul_f32_e32 v19, v16, v17
	v_lshl_add_u64 v[20:21], v[32:33], 1, v[176:177]
	v_cvt_pk_bf16_f32 v16, v24, v25
	v_cvt_pk_bf16_f32 v17, v26, v27
	v_cvt_pk_bf16_f32 v18, v28, v29
	v_cvt_pk_bf16_f32 v19, v22, v19
	ds_write_b128 v184, v[16:19]
	ds_read_b128 v[188:191], v185
	v_mov_b32_e32 v196, v20
	v_mov_b32_e32 v197, v21
	s_waitcnt lgkmcnt(2)
	global_store_dwordx4 v[198:199], v[192:195], off
	s_nop 1
	v_add_u32_e32 v16, 0xb0, v180
	v_ashrrev_i32_e32 v17, 31, v16
	s_waitcnt lgkmcnt(0)
	v_mul_f32_e32 v8, v8, v158
	v_mul_lo_u32 v18, s64, v17
	v_mul_f32_e32 v17, 0xbfb8aa3b, v8
	v_exp_f32_e32 v20, v17
	v_mul_lo_u32 v19, s65, v16
	v_mad_u64_u32 v[16:17], s[0:1], s64, v16, 0
	v_add3_u32 v17, v17, v18, v19
	v_add_f32_e32 v18, 1.0, v20
	v_rcp_f32_e32 v18, v18
	v_mul_f32_e32 v9, v9, v158
	v_mul_f32_e32 v19, 0xbfb8aa3b, v9
	v_exp_f32_e32 v19, v19
	v_mul_f32_e32 v18, v8, v18
	v_mul_f32_e32 v12, v12, v158
	v_cndmask_b32_e64 v8, v18, v8, s[12:13]
	v_mul_f32_e32 v8, v12, v8
	v_add_f32_e32 v12, 1.0, v19
	v_mul_f32_e32 v10, v10, v158
	v_rcp_f32_e32 v12, v12
	v_mul_f32_e32 v18, 0xbfb8aa3b, v10
	v_exp_f32_e32 v18, v18
	v_mul_f32_e32 v11, v11, v158
	v_mul_f32_e32 v12, v9, v12
	v_cndmask_b32_e64 v9, v12, v9, s[12:13]
	v_add_f32_e32 v12, 1.0, v18
	v_mul_f32_e32 v18, 0xbfb8aa3b, v11
	v_exp_f32_e32 v18, v18
	v_mul_f32_e32 v13, v13, v158
	v_rcp_f32_e32 v12, v12
	v_mul_f32_e32 v9, v13, v9
	v_mul_f32_e32 v13, v14, v158
	v_add_f32_e32 v14, 1.0, v18
	v_rcp_f32_e32 v14, v14
	v_mul_f32_e32 v12, v10, v12
	v_cndmask_b32_e64 v10, v12, v10, s[12:13]
	v_mul_f32_e32 v0, v0, v158
	v_mul_f32_e32 v10, v13, v10
	v_mul_f32_e32 v13, v11, v14
	v_mul_f32_e32 v14, 0xbfb8aa3b, v0
	v_exp_f32_e32 v14, v14
	v_mul_f32_e32 v12, v15, v158
	v_cndmask_b32_e64 v11, v13, v11, s[12:13]
	v_mul_f32_e32 v11, v12, v11
	v_add_f32_e32 v12, 1.0, v14
	v_rcp_f32_e32 v12, v12
	v_mul_f32_e32 v1, v1, v158
	v_mul_f32_e32 v13, 0xbfb8aa3b, v1
	v_exp_f32_e32 v13, v13
	v_mul_f32_e32 v12, v0, v12
	v_mul_f32_e32 v4, v4, v158
	v_cndmask_b32_e64 v0, v12, v0, s[12:13]
	v_mul_f32_e32 v12, v4, v0
	v_add_f32_e32 v0, 1.0, v13
	v_mul_f32_e32 v2, v2, v158
	v_rcp_f32_e32 v0, v0
	v_mul_f32_e32 v4, 0xbfb8aa3b, v2
	v_exp_f32_e32 v4, v4
	v_mul_f32_e32 v3, v3, v158
	v_mul_f32_e32 v0, v1, v0
	v_cndmask_b32_e64 v0, v0, v1, s[12:13]
	v_add_f32_e32 v1, 1.0, v4
	v_mul_f32_e32 v4, 0xbfb8aa3b, v3
	v_exp_f32_e32 v4, v4
	v_rcp_f32_e32 v1, v1
	v_mul_f32_e32 v5, v5, v158
	v_mul_f32_e32 v13, v5, v0
	v_add_f32_e32 v4, 1.0, v4
	v_rcp_f32_e32 v4, v4
	v_mul_f32_e32 v1, v2, v1
	v_mul_f32_e32 v0, v6, v158
	v_cndmask_b32_e64 v1, v1, v2, s[12:13]
	v_mul_f32_e32 v6, v0, v1
	v_mul_f32_e32 v1, v3, v4
	v_mul_f32_e32 v0, v7, v158
	v_cndmask_b32_e64 v1, v1, v3, s[12:13]
	v_mul_f32_e32 v3, v0, v1
	v_lshl_add_u64 v[4:5], v[16:17], 1, v[176:177]
	v_cvt_pk_bf16_f32 v0, v8, v9
	v_cvt_pk_bf16_f32 v1, v10, v11
	v_cvt_pk_bf16_f32 v2, v12, v13
	v_cvt_pk_bf16_f32 v3, v6, v3
	ds_write_b128 v184, v[0:3] offset:1024
	ds_read_b128 v[192:195], v185 offset:1024
	v_mov_b32_e32 v198, v4
	v_mov_b32_e32 v199, v5
	s_waitcnt lgkmcnt(2)
	global_store_dwordx4 v[196:197], v[188:191], off
	s_waitcnt lgkmcnt(0)
	global_store_dwordx4 v[198:199], v[192:195], off
	s_andn2_b64 vcc, exec, s[10:11]
	s_mov_b64 s[10:11], -1
	s_cbranch_vccnz .LBB0_691

; __device__ __forceinline__ unsigned cvt_pk_bf16(float lo, float hi) { unsigned r; asm("v_cvt_pk_bf16_f32 %0, %1, %2" : "=v"(r) : "v"(lo), "v"(hi)); return r; }
; __device__ __forceinline__ float silu_f(float x) { return x * __builtin_amdgcn_rcpf(1.f + __builtin_amdgcn_exp2f(-LOG2E * x)); }
;     __device__ __forceinline__ void operator()(const f32x4 (&acc)[2][2][4][2], const Unit& u, int wr, int wc, int fr, int fq, LAS unsigned char* xs, int wid, int lane) const {
;     ...
;         } else if (mode == 1 || mode == 2) {
; #pragma unroll
;             for (int ai = 0; ai < 2; ++ai)
; #pragma unroll
;                 for (int m = 0; m < 4; ++m) {
;                     const float r = rs[ai][m];
;                     bf16_t* rowp = base + (size_t)(row0 + ai * 128 + m * 16 + fr) * ldc + wc * 32 + 8 * fq;
;                     float o[8];
; #pragma unroll
;                     for (int n = 0; n < 2; ++n)
; #pragma unroll
;                         for (int j = 0; j < 4; ++j) { const float a = acc[ai][0][m][n][j] * r, b = acc[ai][1][m][n][j] * r; o[4 * n + j] = (mode == 1) ? a * b : a * silu_f(b); }
;                     u32x4 w; w.x = cvt_pk_bf16(o[0], o[1]); w.y = cvt_pk_bf16(o[2], o[3]); w.z = cvt_pk_bf16(o[4], o[5]); w.w = cvt_pk_bf16(o[6], o[7]);
;                     *(u32x4*)rowp = w;
.LBB0_1494:
	v_and_b32_e32 v186, 63, v254
	v_lshrrev_b32_e32 v180, 2, v186
	v_and_b32_e32 v182, 3, v186
	v_bfe_u32 v185, v186, 4, 2
	v_xor_b32_e32 v185, v182, v185
	v_lshlrev_b32_e32 v185, 4, v185
	v_lshl_add_u32 v185, v180, 6, v185
	v_and_b32_e32 v184, 0x1c0, v254
	v_lshlrev_b32_e32 v184, 6, v184
	v_add_u32_e32 v184, 0x20000, v184
	v_add_u32_e32 v185, v184, v185
	v_and_b32_e32 v186, 15, v186
	v_lshlrev_b32_e32 v186, 6, v186
	v_add_u32_e32 v184, v184, v186
	v_bfe_u32 v186, v254, 4, 2
	v_bfe_u32 v187, v254, 2, 2
	v_xor_b32_e32 v186, v186, v187
	v_lshl_add_u32 v184, v186, 4, v184
	v_or_b32_e32 v180, s56, v180
	v_lshlrev_b32_e32 v182, 4, v182
	v_mov_b32_e32 v183, 0
	s_waitcnt lgkmcnt(7)
	v_mul_f32_e32 v120, v120, v174
	v_mul_f32_e32 v159, 0xbfb8aa3b, v120
	s_add_u32 s0, s58, s75
	v_exp_f32_e32 v159, v159
	s_addc_u32 s1, s59, 0
	v_mov_b32_e32 v151, v137
	v_lshl_add_u64 v[176:177], s[0:1], 0, v[182:183]
	s_ashr_i32 s0, s56, 31
	v_mul_lo_u32 v151, s53, v180
	s_mul_i32 s0, s52, s0
	v_mad_u64_u32 v[178:179], s[54:55], s52, v180, 0
	v_add3_u32 v179, v179, s0, v151
	v_add_f32_e32 v151, 1.0, v159
	v_rcp_f32_e32 v151, v151
	v_mul_f32_e32 v121, v121, v174
	v_mul_f32_e32 v159, 0xbfb8aa3b, v121
	v_exp_f32_e32 v159, v159
	v_mul_f32_e32 v151, v120, v151
	v_mul_f32_e32 v124, v124, v174
	v_cndmask_b32_e64 v120, v151, v120, s[10:11]
	v_mul_f32_e32 v120, v124, v120
	v_add_f32_e32 v124, 1.0, v159
	v_mul_f32_e32 v122, v122, v174
	v_rcp_f32_e32 v124, v124
	v_mul_f32_e32 v151, 0xbfb8aa3b, v122
	v_exp_f32_e32 v151, v151
	v_mul_f32_e32 v123, v123, v174
	v_mul_f32_e32 v124, v121, v124
	v_cndmask_b32_e64 v121, v124, v121, s[10:11]
	v_add_f32_e32 v124, 1.0, v151
	v_mul_f32_e32 v151, 0xbfb8aa3b, v123
	v_exp_f32_e32 v151, v151
	v_mul_f32_e32 v125, v125, v174
	v_rcp_f32_e32 v124, v124
	v_mul_f32_e32 v121, v125, v121
	v_mul_f32_e32 v125, v126, v174
	v_add_f32_e32 v126, 1.0, v151
	v_rcp_f32_e32 v126, v126
	v_mul_f32_e32 v124, v122, v124
	v_cndmask_b32_e64 v122, v124, v122, s[10:11]
	v_mul_f32_e32 v112, v112, v174
	v_mul_f32_e32 v122, v125, v122
	v_mul_f32_e32 v125, v123, v126
	v_mul_f32_e32 v126, 0xbfb8aa3b, v112
	v_exp_f32_e32 v126, v126
	v_mul_f32_e32 v124, v127, v174
	v_cndmask_b32_e64 v123, v125, v123, s[10:11]
	v_mul_f32_e32 v123, v124, v123
	v_add_f32_e32 v124, 1.0, v126
	v_rcp_f32_e32 v124, v124
	v_mul_f32_e32 v113, v113, v174
	v_mul_f32_e32 v125, 0xbfb8aa3b, v113
	v_exp_f32_e32 v125, v125
	v_mul_f32_e32 v124, v112, v124
	v_mul_f32_e32 v116, v116, v174
	v_cndmask_b32_e64 v112, v124, v112, s[10:11]
	v_mul_f32_e32 v124, v116, v112
	v_add_f32_e32 v112, 1.0, v125
	v_mul_f32_e32 v114, v114, v174
	v_rcp_f32_e32 v112, v112
	v_mul_f32_e32 v116, 0xbfb8aa3b, v114
	v_exp_f32_e32 v116, v116
	v_mul_f32_e32 v115, v115, v174
	v_mul_f32_e32 v112, v113, v112
	v_cndmask_b32_e64 v112, v112, v113, s[10:11]
	v_add_f32_e32 v113, 1.0, v116
	v_mul_f32_e32 v116, 0xbfb8aa3b, v115
	v_exp_f32_e32 v116, v116
	v_rcp_f32_e32 v113, v113
	v_mul_f32_e32 v117, v117, v174
	v_mul_f32_e32 v125, v117, v112
	v_add_f32_e32 v116, 1.0, v116
	v_rcp_f32_e32 v116, v116
	v_mul_f32_e32 v113, v114, v113
	v_mul_f32_e32 v112, v118, v174
	v_cndmask_b32_e64 v113, v113, v114, s[10:11]
	v_mul_f32_e32 v118, v112, v113
	v_mul_f32_e32 v113, v115, v116
	v_mul_f32_e32 v112, v119, v174
	v_cndmask_b32_e64 v113, v113, v115, s[10:11]
	v_mul_f32_e32 v115, v112, v113
	v_lshl_add_u64 v[116:117], v[178:179], 1, v[176:177]
	v_cvt_pk_bf16_f32 v112, v120, v121
	v_cvt_pk_bf16_f32 v113, v122, v123
	v_cvt_pk_bf16_f32 v114, v124, v125
	v_cvt_pk_bf16_f32 v115, v118, v115
	ds_write_b128 v184, v[112:115]
	ds_read_b128 v[188:191], v185
	v_mov_b32_e32 v196, v116
	v_mov_b32_e32 v197, v117
	s_waitcnt lgkmcnt(6)
	v_mul_f32_e32 v104, v104, v172
	v_mul_f32_e32 v113, 0xbfb8aa3b, v104
	v_exp_f32_e32 v115, v113
	v_or_b32_e32 v112, 16, v180
	v_mul_lo_u32 v114, s53, v112
	v_mad_u64_u32 v[112:113], s[54:55], s52, v112, 0
	v_add3_u32 v113, v113, s0, v114
	v_add_f32_e32 v114, 1.0, v115
	v_rcp_f32_e32 v114, v114
	v_mul_f32_e32 v105, v105, v172
	v_mul_f32_e32 v115, 0xbfb8aa3b, v105
	v_exp_f32_e32 v115, v115
	v_mul_f32_e32 v114, v104, v114
	v_mul_f32_e32 v108, v108, v172
	v_cndmask_b32_e64 v104, v114, v104, s[10:11]
	v_mul_f32_e32 v104, v108, v104
	v_add_f32_e32 v108, 1.0, v115
	v_mul_f32_e32 v106, v106, v172
	v_rcp_f32_e32 v108, v108
	v_mul_f32_e32 v114, 0xbfb8aa3b, v106
	v_exp_f32_e32 v114, v114
	v_mul_f32_e32 v107, v107, v172
	v_mul_f32_e32 v108, v105, v108
	v_cndmask_b32_e64 v105, v108, v105, s[10:11]
	v_add_f32_e32 v108, 1.0, v114
	v_mul_f32_e32 v114, 0xbfb8aa3b, v107
	v_exp_f32_e32 v114, v114
	v_mul_f32_e32 v109, v109, v172
	v_rcp_f32_e32 v108, v108
	v_mul_f32_e32 v105, v109, v105
	v_mul_f32_e32 v109, v110, v172
	v_add_f32_e32 v110, 1.0, v114
	v_rcp_f32_e32 v110, v110
	v_mul_f32_e32 v108, v106, v108
	v_cndmask_b32_e64 v106, v108, v106, s[10:11]
	v_mul_f32_e32 v96, v96, v172
	v_mul_f32_e32 v106, v109, v106
	v_mul_f32_e32 v109, v107, v110
	v_mul_f32_e32 v110, 0xbfb8aa3b, v96
	v_exp_f32_e32 v110, v110
	v_mul_f32_e32 v108, v111, v172
	v_cndmask_b32_e64 v107, v109, v107, s[10:11]
	v_mul_f32_e32 v107, v108, v107
	v_add_f32_e32 v108, 1.0, v110
	v_rcp_f32_e32 v108, v108
	v_mul_f32_e32 v97, v97, v172
	v_mul_f32_e32 v109, 0xbfb8aa3b, v97
	v_exp_f32_e32 v109, v109
	v_mul_f32_e32 v108, v96, v108
	v_mul_f32_e32 v100, v100, v172
	v_cndmask_b32_e64 v96, v108, v96, s[10:11]
	v_mul_f32_e32 v108, v100, v96
	v_add_f32_e32 v96, 1.0, v109
	v_mul_f32_e32 v98, v98, v172
	v_rcp_f32_e32 v96, v96
	v_mul_f32_e32 v100, 0xbfb8aa3b, v98
	v_exp_f32_e32 v100, v100
	v_mul_f32_e32 v99, v99, v172
	v_mul_f32_e32 v96, v97, v96
	v_cndmask_b32_e64 v96, v96, v97, s[10:11]
	v_add_f32_e32 v97, 1.0, v100
	v_mul_f32_e32 v100, 0xbfb8aa3b, v99
	v_exp_f32_e32 v100, v100
	v_rcp_f32_e32 v97, v97
	v_mul_f32_e32 v101, v101, v172
	v_mul_f32_e32 v109, v101, v96
	v_add_f32_e32 v100, 1.0, v100
	v_rcp_f32_e32 v100, v100
	v_mul_f32_e32 v97, v98, v97
	v_mul_f32_e32 v96, v102, v172
	v_cndmask_b32_e64 v97, v97, v98, s[10:11]
	v_mul_f32_e32 v102, v96, v97
	v_mul_f32_e32 v97, v99, v100
	v_mul_f32_e32 v96, v103, v172
	v_cndmask_b32_e64 v97, v97, v99, s[10:11]
	v_mul_f32_e32 v99, v96, v97
	v_lshl_add_u64 v[100:101], v[112:113], 1, v[176:177]
	v_cvt_pk_bf16_f32 v96, v104, v105
	v_cvt_pk_bf16_f32 v97, v106, v107
	v_cvt_pk_bf16_f32 v98, v108, v109
	v_cvt_pk_bf16_f32 v99, v102, v99
	ds_write_b128 v184, v[96:99] offset:1024
	ds_read_b128 v[192:195], v185 offset:1024
	v_mov_b32_e32 v198, v100
	v_mov_b32_e32 v199, v101
	s_waitcnt lgkmcnt(2)
; __device__ __forceinline__ unsigned cvt_pk_bf16(float lo, float hi) { unsigned r; asm("v_cvt_pk_bf16_f32 %0, %1, %2" : "=v"(r) : "v"(lo), "v"(hi)); return r; }
; __device__ __forceinline__ float silu_f(float x) { return x * __builtin_amdgcn_rcpf(1.f + __builtin_amdgcn_exp2f(-LOG2E * x)); }
;     __device__ __forceinline__ void operator()(const f32x4 (&acc)[2][2][4][2], const Unit& u, int wr, int wc, int fr, int fq, LAS unsigned char* xs, int wid, int lane) const {
;     ...
;                 for (int m = 0; m < 4; ++m) {
;                     const float r = rs[ai][m];
;                     bf16_t* rowp = base + (size_t)(row0 + ai * 128 + m * 16 + fr) * ldc + wc * 32 + 8 * fq;
;                     float o[8];
; #pragma unroll
;                     for (int n = 0; n < 2; ++n)
; #pragma unroll
;                         for (int j = 0; j < 4; ++j) { const float a = acc[ai][0][m][n][j] * r, b = acc[ai][1][m][n][j] * r; o[4 * n + j] = (mode == 1) ? a * b : a * silu_f(b); }
;                     u32x4 w; w.x = cvt_pk_bf16(o[0], o[1]); w.y = cvt_pk_bf16(o[2], o[3]); w.z = cvt_pk_bf16(o[4], o[5]); w.w = cvt_pk_bf16(o[6], o[7]);
;                     *(u32x4*)rowp = w;
	global_store_dwordx4 v[196:197], v[188:191], off
	s_waitcnt lgkmcnt(5)
	v_mul_f32_e32 v88, v88, v170
	v_mul_f32_e32 v97, 0xbfb8aa3b, v88
	v_exp_f32_e32 v99, v97
	v_or_b32_e32 v96, 32, v180
	v_mul_lo_u32 v98, s53, v96
	v_mad_u64_u32 v[96:97], s[54:55], s52, v96, 0
	v_add3_u32 v97, v97, s0, v98
	v_add_f32_e32 v98, 1.0, v99
	v_rcp_f32_e32 v98, v98
	v_mul_f32_e32 v89, v89, v170
	v_mul_f32_e32 v99, 0xbfb8aa3b, v89
	v_exp_f32_e32 v99, v99
	v_mul_f32_e32 v98, v88, v98
	v_mul_f32_e32 v92, v92, v170
	v_cndmask_b32_e64 v88, v98, v88, s[10:11]
	v_mul_f32_e32 v88, v92, v88
	v_add_f32_e32 v92, 1.0, v99
	v_mul_f32_e32 v90, v90, v170
	v_rcp_f32_e32 v92, v92
	v_mul_f32_e32 v98, 0xbfb8aa3b, v90
	v_exp_f32_e32 v98, v98
	v_mul_f32_e32 v91, v91, v170
	v_mul_f32_e32 v92, v89, v92
	v_cndmask_b32_e64 v89, v92, v89, s[10:11]
	v_add_f32_e32 v92, 1.0, v98
	v_mul_f32_e32 v98, 0xbfb8aa3b, v91
	v_exp_f32_e32 v98, v98
	v_mul_f32_e32 v93, v93, v170
	v_rcp_f32_e32 v92, v92
	v_mul_f32_e32 v89, v93, v89
	v_mul_f32_e32 v93, v94, v170
	v_add_f32_e32 v94, 1.0, v98
	v_rcp_f32_e32 v94, v94
	v_mul_f32_e32 v92, v90, v92
	v_cndmask_b32_e64 v90, v92, v90, s[10:11]
	v_mul_f32_e32 v80, v80, v170
	v_mul_f32_e32 v90, v93, v90
	v_mul_f32_e32 v93, v91, v94
	v_mul_f32_e32 v94, 0xbfb8aa3b, v80
	v_exp_f32_e32 v94, v94
	v_mul_f32_e32 v92, v95, v170
	v_cndmask_b32_e64 v91, v93, v91, s[10:11]
	v_mul_f32_e32 v91, v92, v91
	v_add_f32_e32 v92, 1.0, v94
	v_rcp_f32_e32 v92, v92
	v_mul_f32_e32 v81, v81, v170
	v_mul_f32_e32 v93, 0xbfb8aa3b, v81
	v_exp_f32_e32 v93, v93
	v_mul_f32_e32 v92, v80, v92
	v_mul_f32_e32 v84, v84, v170
	v_cndmask_b32_e64 v80, v92, v80, s[10:11]
	v_mul_f32_e32 v92, v84, v80
	v_add_f32_e32 v80, 1.0, v93
	v_mul_f32_e32 v82, v82, v170
	v_rcp_f32_e32 v80, v80
	v_mul_f32_e32 v84, 0xbfb8aa3b, v82
	v_exp_f32_e32 v84, v84
	v_mul_f32_e32 v83, v83, v170
	v_mul_f32_e32 v80, v81, v80
	v_cndmask_b32_e64 v80, v80, v81, s[10:11]
	v_add_f32_e32 v81, 1.0, v84
	v_mul_f32_e32 v84, 0xbfb8aa3b, v83
	v_exp_f32_e32 v84, v84
	v_rcp_f32_e32 v81, v81
	v_mul_f32_e32 v85, v85, v170
	v_mul_f32_e32 v93, v85, v80
	v_add_f32_e32 v84, 1.0, v84
	v_rcp_f32_e32 v84, v84
	v_mul_f32_e32 v81, v82, v81
	v_mul_f32_e32 v80, v86, v170
	v_cndmask_b32_e64 v81, v81, v82, s[10:11]
	v_mul_f32_e32 v86, v80, v81
	v_mul_f32_e32 v81, v83, v84
	v_mul_f32_e32 v80, v87, v170
	v_cndmask_b32_e64 v81, v81, v83, s[10:11]
	v_mul_f32_e32 v83, v80, v81
	v_lshl_add_u64 v[84:85], v[96:97], 1, v[176:177]
	v_cvt_pk_bf16_f32 v80, v88, v89
	v_cvt_pk_bf16_f32 v81, v90, v91
	v_cvt_pk_bf16_f32 v82, v92, v93
	v_cvt_pk_bf16_f32 v83, v86, v83
	ds_write_b128 v184, v[80:83]
	ds_read_b128 v[188:191], v185
	v_mov_b32_e32 v196, v84
	v_mov_b32_e32 v197, v85
	s_waitcnt lgkmcnt(2)
	global_store_dwordx4 v[198:199], v[192:195], off
	s_waitcnt lgkmcnt(4)
	v_mul_f32_e32 v72, v72, v168
	v_mul_f32_e32 v81, 0xbfb8aa3b, v72
	v_exp_f32_e32 v83, v81
	v_or_b32_e32 v80, 48, v180
	v_mul_lo_u32 v82, s53, v80
	v_mad_u64_u32 v[80:81], s[54:55], s52, v80, 0
	v_add3_u32 v81, v81, s0, v82
	v_add_f32_e32 v82, 1.0, v83
	v_rcp_f32_e32 v82, v82
	v_mul_f32_e32 v73, v73, v168
	v_mul_f32_e32 v83, 0xbfb8aa3b, v73
	v_exp_f32_e32 v83, v83
	v_mul_f32_e32 v82, v72, v82
	v_mul_f32_e32 v76, v76, v168
	v_cndmask_b32_e64 v72, v82, v72, s[10:11]
	v_mul_f32_e32 v72, v76, v72
	v_add_f32_e32 v76, 1.0, v83
	v_mul_f32_e32 v74, v74, v168
	v_rcp_f32_e32 v76, v76
	v_mul_f32_e32 v82, 0xbfb8aa3b, v74
	v_exp_f32_e32 v82, v82
	v_mul_f32_e32 v75, v75, v168
	v_mul_f32_e32 v76, v73, v76
	v_cndmask_b32_e64 v73, v76, v73, s[10:11]
	v_add_f32_e32 v76, 1.0, v82
	v_mul_f32_e32 v82, 0xbfb8aa3b, v75
	v_exp_f32_e32 v82, v82
	v_mul_f32_e32 v77, v77, v168
	v_rcp_f32_e32 v76, v76
	v_mul_f32_e32 v73, v77, v73
	v_mul_f32_e32 v77, v78, v168
	v_add_f32_e32 v78, 1.0, v82
	v_rcp_f32_e32 v78, v78
	v_mul_f32_e32 v76, v74, v76
	v_cndmask_b32_e64 v74, v76, v74, s[10:11]
	v_mul_f32_e32 v64, v64, v168
	v_mul_f32_e32 v74, v77, v74
	v_mul_f32_e32 v77, v75, v78
	v_mul_f32_e32 v78, 0xbfb8aa3b, v64
	v_exp_f32_e32 v78, v78
	v_mul_f32_e32 v76, v79, v168
	v_cndmask_b32_e64 v75, v77, v75, s[10:11]
	v_mul_f32_e32 v75, v76, v75
	v_add_f32_e32 v76, 1.0, v78
	v_rcp_f32_e32 v76, v76
	v_mul_f32_e32 v65, v65, v168
	v_mul_f32_e32 v77, 0xbfb8aa3b, v65
	v_exp_f32_e32 v77, v77
	v_mul_f32_e32 v76, v64, v76
	v_mul_f32_e32 v68, v68, v168
	v_cndmask_b32_e64 v64, v76, v64, s[10:11]
	v_mul_f32_e32 v76, v68, v64
	v_add_f32_e32 v64, 1.0, v77
	v_mul_f32_e32 v66, v66, v168
	v_rcp_f32_e32 v64, v64
	v_mul_f32_e32 v68, 0xbfb8aa3b, v66
	v_exp_f32_e32 v68, v68
	v_mul_f32_e32 v67, v67, v168
	v_mul_f32_e32 v64, v65, v64
	v_cndmask_b32_e64 v64, v64, v65, s[10:11]
	v_add_f32_e32 v65, 1.0, v68
	v_mul_f32_e32 v68, 0xbfb8aa3b, v67
	v_exp_f32_e32 v68, v68
	v_rcp_f32_e32 v65, v65
	v_mul_f32_e32 v69, v69, v168
	v_mul_f32_e32 v77, v69, v64
	v_add_f32_e32 v68, 1.0, v68
	v_rcp_f32_e32 v68, v68
	v_mul_f32_e32 v65, v66, v65
	v_mul_f32_e32 v64, v70, v168
	v_cndmask_b32_e64 v65, v65, v66, s[10:11]
	v_mul_f32_e32 v70, v64, v65
	v_mul_f32_e32 v65, v67, v68
	v_mul_f32_e32 v64, v71, v168
	v_cndmask_b32_e64 v65, v65, v67, s[10:11]
	v_mul_f32_e32 v67, v64, v65
	v_lshl_add_u64 v[68:69], v[80:81], 1, v[176:177]
	v_cvt_pk_bf16_f32 v64, v72, v73
	v_cvt_pk_bf16_f32 v65, v74, v75
	v_cvt_pk_bf16_f32 v66, v76, v77
	v_cvt_pk_bf16_f32 v67, v70, v67
	ds_write_b128 v184, v[64:67] offset:1024
	ds_read_b128 v[192:195], v185 offset:1024
	v_mov_b32_e32 v198, v68
	v_mov_b32_e32 v199, v69
	s_waitcnt lgkmcnt(2)
	global_store_dwordx4 v[196:197], v[188:191], off
	s_nop 1
	v_add_u32_e32 v64, 0x80, v180
	v_ashrrev_i32_e32 v65, 31, v64
	s_waitcnt lgkmcnt(3)
; __device__ __forceinline__ unsigned cvt_pk_bf16(float lo, float hi) { unsigned r; asm("v_cvt_pk_bf16_f32 %0, %1, %2" : "=v"(r) : "v"(lo), "v"(hi)); return r; }
; __device__ __forceinline__ float silu_f(float x) { return x * __builtin_amdgcn_rcpf(1.f + __builtin_amdgcn_exp2f(-LOG2E * x)); }
;     __device__ __forceinline__ void operator()(const f32x4 (&acc)[2][2][4][2], const Unit& u, int wr, int wc, int fr, int fq, LAS unsigned char* xs, int wid, int lane) const {
;     ...
;                 for (int m = 0; m < 4; ++m) {
;                     const float r = rs[ai][m];
;                     bf16_t* rowp = base + (size_t)(row0 + ai * 128 + m * 16 + fr) * ldc + wc * 32 + 8 * fq;
;                     float o[8];
; #pragma unroll
;                     for (int n = 0; n < 2; ++n)
; #pragma unroll
;                         for (int j = 0; j < 4; ++j) { const float a = acc[ai][0][m][n][j] * r, b = acc[ai][1][m][n][j] * r; o[4 * n + j] = (mode == 1) ? a * b : a * silu_f(b); }
;                     u32x4 w; w.x = cvt_pk_bf16(o[0], o[1]); w.y = cvt_pk_bf16(o[2], o[3]); w.z = cvt_pk_bf16(o[4], o[5]); w.w = cvt_pk_bf16(o[6], o[7]);
;                     *(u32x4*)rowp = w;
	v_mul_f32_e32 v56, v56, v166
	v_mul_lo_u32 v66, s52, v65
	v_mul_f32_e32 v65, 0xbfb8aa3b, v56
	v_exp_f32_e32 v68, v65
	v_mul_lo_u32 v67, s53, v64
	v_mad_u64_u32 v[64:65], s[0:1], s52, v64, 0
	v_add3_u32 v65, v65, v66, v67
	v_add_f32_e32 v66, 1.0, v68
	v_rcp_f32_e32 v66, v66
	v_mul_f32_e32 v57, v57, v166
	v_mul_f32_e32 v67, 0xbfb8aa3b, v57
	v_exp_f32_e32 v67, v67
	v_mul_f32_e32 v66, v56, v66
	v_mul_f32_e32 v60, v60, v166
	v_cndmask_b32_e64 v56, v66, v56, s[10:11]
	v_mul_f32_e32 v56, v60, v56
	v_add_f32_e32 v60, 1.0, v67
	v_mul_f32_e32 v58, v58, v166
	v_rcp_f32_e32 v60, v60
	v_mul_f32_e32 v66, 0xbfb8aa3b, v58
	v_exp_f32_e32 v66, v66
	v_mul_f32_e32 v59, v59, v166
	v_mul_f32_e32 v60, v57, v60
	v_cndmask_b32_e64 v57, v60, v57, s[10:11]
	v_add_f32_e32 v60, 1.0, v66
	v_mul_f32_e32 v66, 0xbfb8aa3b, v59
	v_exp_f32_e32 v66, v66
	v_mul_f32_e32 v61, v61, v166
	v_rcp_f32_e32 v60, v60
	v_mul_f32_e32 v57, v61, v57
	v_mul_f32_e32 v61, v62, v166
	v_add_f32_e32 v62, 1.0, v66
	v_rcp_f32_e32 v62, v62
	v_mul_f32_e32 v60, v58, v60
	v_cndmask_b32_e64 v58, v60, v58, s[10:11]
	v_mul_f32_e32 v48, v48, v166
	v_mul_f32_e32 v58, v61, v58
	v_mul_f32_e32 v61, v59, v62
	v_mul_f32_e32 v62, 0xbfb8aa3b, v48
	v_exp_f32_e32 v62, v62
	v_mul_f32_e32 v60, v63, v166
	v_cndmask_b32_e64 v59, v61, v59, s[10:11]
	v_mul_f32_e32 v59, v60, v59
	v_add_f32_e32 v60, 1.0, v62
	v_rcp_f32_e32 v60, v60
	v_mul_f32_e32 v49, v49, v166
	v_mul_f32_e32 v61, 0xbfb8aa3b, v49
	v_exp_f32_e32 v61, v61
	v_mul_f32_e32 v60, v48, v60
	v_mul_f32_e32 v52, v52, v166
	v_cndmask_b32_e64 v48, v60, v48, s[10:11]
	v_mul_f32_e32 v60, v52, v48
	v_add_f32_e32 v48, 1.0, v61
	v_mul_f32_e32 v50, v50, v166
	v_rcp_f32_e32 v48, v48
	v_mul_f32_e32 v52, 0xbfb8aa3b, v50
	v_exp_f32_e32 v52, v52
	v_mul_f32_e32 v51, v51, v166
	v_mul_f32_e32 v48, v49, v48
	v_cndmask_b32_e64 v48, v48, v49, s[10:11]
	v_add_f32_e32 v49, 1.0, v52
	v_mul_f32_e32 v52, 0xbfb8aa3b, v51
	v_exp_f32_e32 v52, v52
	v_rcp_f32_e32 v49, v49
	v_mul_f32_e32 v53, v53, v166
	v_mul_f32_e32 v61, v53, v48
	v_add_f32_e32 v52, 1.0, v52
	v_rcp_f32_e32 v52, v52
	v_mul_f32_e32 v49, v50, v49
	v_mul_f32_e32 v48, v54, v166
	v_cndmask_b32_e64 v49, v49, v50, s[10:11]
	v_mul_f32_e32 v54, v48, v49
	v_mul_f32_e32 v49, v51, v52
	v_mul_f32_e32 v48, v55, v166
	v_cndmask_b32_e64 v49, v49, v51, s[10:11]
	v_mul_f32_e32 v51, v48, v49
	v_lshl_add_u64 v[52:53], v[64:65], 1, v[176:177]
	v_cvt_pk_bf16_f32 v48, v56, v57
	v_cvt_pk_bf16_f32 v49, v58, v59
	v_cvt_pk_bf16_f32 v50, v60, v61
	v_cvt_pk_bf16_f32 v51, v54, v51
	ds_write_b128 v184, v[48:51]
	ds_read_b128 v[188:191], v185
	v_mov_b32_e32 v196, v52
	v_mov_b32_e32 v197, v53
	s_waitcnt lgkmcnt(2)
	global_store_dwordx4 v[198:199], v[192:195], off
	s_nop 1
	v_add_u32_e32 v48, 0x90, v180
	v_ashrrev_i32_e32 v49, 31, v48
	s_waitcnt lgkmcnt(2)
	v_mul_f32_e32 v40, v40, v164
	v_mul_lo_u32 v50, s52, v49
	v_mul_f32_e32 v49, 0xbfb8aa3b, v40
	v_exp_f32_e32 v52, v49
	v_mul_lo_u32 v51, s53, v48
	v_mad_u64_u32 v[48:49], s[0:1], s52, v48, 0
	v_add3_u32 v49, v49, v50, v51
	v_add_f32_e32 v50, 1.0, v52
	v_rcp_f32_e32 v50, v50
	v_mul_f32_e32 v41, v41, v164
	v_mul_f32_e32 v51, 0xbfb8aa3b, v41
	v_exp_f32_e32 v51, v51
	v_mul_f32_e32 v50, v40, v50
	v_mul_f32_e32 v44, v44, v164
	v_cndmask_b32_e64 v40, v50, v40, s[10:11]
	v_mul_f32_e32 v40, v44, v40
	v_add_f32_e32 v44, 1.0, v51
	v_mul_f32_e32 v42, v42, v164
	v_rcp_f32_e32 v44, v44
	v_mul_f32_e32 v50, 0xbfb8aa3b, v42
	v_exp_f32_e32 v50, v50
	v_mul_f32_e32 v43, v43, v164
	v_mul_f32_e32 v44, v41, v44
	v_cndmask_b32_e64 v41, v44, v41, s[10:11]
	v_add_f32_e32 v44, 1.0, v50
	v_mul_f32_e32 v50, 0xbfb8aa3b, v43
	v_exp_f32_e32 v50, v50
	v_mul_f32_e32 v45, v45, v164
	v_rcp_f32_e32 v44, v44
	v_mul_f32_e32 v41, v45, v41
	v_mul_f32_e32 v45, v46, v164
	v_add_f32_e32 v46, 1.0, v50
	v_rcp_f32_e32 v46, v46
	v_mul_f32_e32 v44, v42, v44
	v_cndmask_b32_e64 v42, v44, v42, s[10:11]
	v_mul_f32_e32 v32, v32, v164
	v_mul_f32_e32 v42, v45, v42
	v_mul_f32_e32 v45, v43, v46
	v_mul_f32_e32 v46, 0xbfb8aa3b, v32
	v_exp_f32_e32 v46, v46
	v_mul_f32_e32 v44, v47, v164
	v_cndmask_b32_e64 v43, v45, v43, s[10:11]
	v_mul_f32_e32 v43, v44, v43
	v_add_f32_e32 v44, 1.0, v46
	v_rcp_f32_e32 v44, v44
	v_mul_f32_e32 v33, v33, v164
	v_mul_f32_e32 v45, 0xbfb8aa3b, v33
	v_exp_f32_e32 v45, v45
	v_mul_f32_e32 v44, v32, v44
	v_mul_f32_e32 v36, v36, v164
	v_cndmask_b32_e64 v32, v44, v32, s[10:11]
	v_mul_f32_e32 v44, v36, v32
	v_add_f32_e32 v32, 1.0, v45
	v_mul_f32_e32 v34, v34, v164
	v_rcp_f32_e32 v32, v32
	v_mul_f32_e32 v36, 0xbfb8aa3b, v34
	v_exp_f32_e32 v36, v36
	v_mul_f32_e32 v35, v35, v164
	v_mul_f32_e32 v32, v33, v32
	v_cndmask_b32_e64 v32, v32, v33, s[10:11]
	v_add_f32_e32 v33, 1.0, v36
	v_mul_f32_e32 v36, 0xbfb8aa3b, v35
	v_exp_f32_e32 v36, v36
	v_rcp_f32_e32 v33, v33
	v_mul_f32_e32 v37, v37, v164
	v_mul_f32_e32 v45, v37, v32
	v_add_f32_e32 v36, 1.0, v36
	v_rcp_f32_e32 v36, v36
	v_mul_f32_e32 v33, v34, v33
	v_mul_f32_e32 v32, v38, v164
	v_cndmask_b32_e64 v33, v33, v34, s[10:11]
	v_mul_f32_e32 v38, v32, v33
	v_mul_f32_e32 v33, v35, v36
	v_mul_f32_e32 v32, v39, v164
	v_cndmask_b32_e64 v33, v33, v35, s[10:11]
	v_mul_f32_e32 v35, v32, v33
	v_lshl_add_u64 v[36:37], v[48:49], 1, v[176:177]
	v_cvt_pk_bf16_f32 v32, v40, v41
	v_cvt_pk_bf16_f32 v33, v42, v43
	v_cvt_pk_bf16_f32 v34, v44, v45
	v_cvt_pk_bf16_f32 v35, v38, v35
	ds_write_b128 v184, v[32:35] offset:1024
	ds_read_b128 v[192:195], v185 offset:1024
	v_mov_b32_e32 v198, v36
	v_mov_b32_e32 v199, v37
	s_waitcnt lgkmcnt(2)
	global_store_dwordx4 v[196:197], v[188:191], off
	s_nop 1
	v_add_u32_e32 v32, 0xa0, v180
	v_ashrrev_i32_e32 v33, 31, v32
	s_waitcnt lgkmcnt(1)
; __device__ __forceinline__ unsigned cvt_pk_bf16(float lo, float hi) { unsigned r; asm("v_cvt_pk_bf16_f32 %0, %1, %2" : "=v"(r) : "v"(lo), "v"(hi)); return r; }
; __device__ __forceinline__ float silu_f(float x) { return x * __builtin_amdgcn_rcpf(1.f + __builtin_amdgcn_exp2f(-LOG2E * x)); }
;     __device__ __forceinline__ void operator()(const f32x4 (&acc)[2][2][4][2], const Unit& u, int wr, int wc, int fr, int fq, LAS unsigned char* xs, int wid, int lane) const {
;     ...
;                 for (int m = 0; m < 4; ++m) {
;                     const float r = rs[ai][m];
;                     bf16_t* rowp = base + (size_t)(row0 + ai * 128 + m * 16 + fr) * ldc + wc * 32 + 8 * fq;
;                     float o[8];
; #pragma unroll
;                     for (int n = 0; n < 2; ++n)
; #pragma unroll
;                         for (int j = 0; j < 4; ++j) { const float a = acc[ai][0][m][n][j] * r, b = acc[ai][1][m][n][j] * r; o[4 * n + j] = (mode == 1) ? a * b : a * silu_f(b); }
;                     u32x4 w; w.x = cvt_pk_bf16(o[0], o[1]); w.y = cvt_pk_bf16(o[2], o[3]); w.z = cvt_pk_bf16(o[4], o[5]); w.w = cvt_pk_bf16(o[6], o[7]);
;                     *(u32x4*)rowp = w;
;                     __builtin_amdgcn_sched_barrier(0);
;                 }
	v_mul_f32_e32 v24, v24, v160
	v_mul_lo_u32 v34, s52, v33
	v_mul_f32_e32 v33, 0xbfb8aa3b, v24
	v_exp_f32_e32 v36, v33
	v_mul_lo_u32 v35, s53, v32
	v_mad_u64_u32 v[32:33], s[0:1], s52, v32, 0
	v_add3_u32 v33, v33, v34, v35
	v_add_f32_e32 v34, 1.0, v36
	v_rcp_f32_e32 v34, v34
	v_mul_f32_e32 v25, v25, v160
	v_mul_f32_e32 v35, 0xbfb8aa3b, v25
	v_exp_f32_e32 v35, v35
	v_mul_f32_e32 v34, v24, v34
	v_mul_f32_e32 v28, v28, v160
	v_cndmask_b32_e64 v24, v34, v24, s[10:11]
	v_mul_f32_e32 v24, v28, v24
	v_add_f32_e32 v28, 1.0, v35
	v_mul_f32_e32 v26, v26, v160
	v_rcp_f32_e32 v28, v28
	v_mul_f32_e32 v34, 0xbfb8aa3b, v26
	v_exp_f32_e32 v34, v34
	v_mul_f32_e32 v27, v27, v160
	v_mul_f32_e32 v28, v25, v28
	v_cndmask_b32_e64 v25, v28, v25, s[10:11]
	v_add_f32_e32 v28, 1.0, v34
	v_mul_f32_e32 v34, 0xbfb8aa3b, v27
	v_exp_f32_e32 v34, v34
	v_mul_f32_e32 v29, v29, v160
	v_rcp_f32_e32 v28, v28
	v_mul_f32_e32 v25, v29, v25
	v_mul_f32_e32 v29, v30, v160
	v_add_f32_e32 v30, 1.0, v34
	v_rcp_f32_e32 v30, v30
	v_mul_f32_e32 v28, v26, v28
	v_cndmask_b32_e64 v26, v28, v26, s[10:11]
	v_mul_f32_e32 v16, v16, v160
	v_mul_f32_e32 v26, v29, v26
	v_mul_f32_e32 v29, v27, v30
	v_mul_f32_e32 v30, 0xbfb8aa3b, v16
	v_exp_f32_e32 v30, v30
	v_mul_f32_e32 v28, v31, v160
	v_cndmask_b32_e64 v27, v29, v27, s[10:11]
	v_mul_f32_e32 v27, v28, v27
	v_add_f32_e32 v28, 1.0, v30
	v_rcp_f32_e32 v28, v28
	v_mul_f32_e32 v17, v17, v160
	v_mul_f32_e32 v29, 0xbfb8aa3b, v17
	v_exp_f32_e32 v29, v29
	v_mul_f32_e32 v28, v16, v28
	v_mul_f32_e32 v20, v20, v160
	v_cndmask_b32_e64 v16, v28, v16, s[10:11]
	v_mul_f32_e32 v28, v20, v16
	v_add_f32_e32 v16, 1.0, v29
	v_mul_f32_e32 v18, v18, v160
	v_rcp_f32_e32 v16, v16
	v_mul_f32_e32 v20, 0xbfb8aa3b, v18
	v_exp_f32_e32 v20, v20
	v_mul_f32_e32 v19, v19, v160
	v_mul_f32_e32 v16, v17, v16
	v_cndmask_b32_e64 v16, v16, v17, s[10:11]
	v_add_f32_e32 v17, 1.0, v20
	v_mul_f32_e32 v20, 0xbfb8aa3b, v19
	v_exp_f32_e32 v20, v20
	v_rcp_f32_e32 v17, v17
	v_mul_f32_e32 v21, v21, v160
	v_mul_f32_e32 v29, v21, v16
	v_add_f32_e32 v20, 1.0, v20
	v_rcp_f32_e32 v20, v20
	v_mul_f32_e32 v17, v18, v17
	v_mul_f32_e32 v16, v22, v160
	v_cndmask_b32_e64 v17, v17, v18, s[10:11]
	v_mul_f32_e32 v22, v16, v17
	v_mul_f32_e32 v17, v19, v20
	v_mul_f32_e32 v16, v23, v160
	v_cndmask_b32_e64 v17, v17, v19, s[10:11]
	v_mul_f32_e32 v19, v16, v17
	v_lshl_add_u64 v[20:21], v[32:33], 1, v[176:177]
	v_cvt_pk_bf16_f32 v16, v24, v25
	v_cvt_pk_bf16_f32 v17, v26, v27
	v_cvt_pk_bf16_f32 v18, v28, v29
	v_cvt_pk_bf16_f32 v19, v22, v19
	ds_write_b128 v184, v[16:19]
	ds_read_b128 v[188:191], v185
	v_mov_b32_e32 v196, v20
	v_mov_b32_e32 v197, v21
	s_waitcnt lgkmcnt(2)
	global_store_dwordx4 v[198:199], v[192:195], off
	s_nop 1
	v_add_u32_e32 v16, 0xb0, v180
	v_ashrrev_i32_e32 v17, 31, v16
	s_waitcnt lgkmcnt(0)
	v_mul_f32_e32 v8, v8, v158
	v_mul_lo_u32 v18, s52, v17
	v_mul_f32_e32 v17, 0xbfb8aa3b, v8
	v_exp_f32_e32 v20, v17
	v_mul_lo_u32 v19, s53, v16
	v_mad_u64_u32 v[16:17], s[0:1], s52, v16, 0
	v_add3_u32 v17, v17, v18, v19
	v_add_f32_e32 v18, 1.0, v20
	v_rcp_f32_e32 v18, v18
	v_mul_f32_e32 v9, v9, v158
	v_mul_f32_e32 v19, 0xbfb8aa3b, v9
	v_exp_f32_e32 v19, v19
	v_mul_f32_e32 v18, v8, v18
	v_mul_f32_e32 v12, v12, v158
	v_cndmask_b32_e64 v8, v18, v8, s[10:11]
	v_mul_f32_e32 v8, v12, v8
	v_add_f32_e32 v12, 1.0, v19
	v_mul_f32_e32 v10, v10, v158
	v_rcp_f32_e32 v12, v12
	v_mul_f32_e32 v18, 0xbfb8aa3b, v10
	v_exp_f32_e32 v18, v18
	v_mul_f32_e32 v11, v11, v158
	v_mul_f32_e32 v12, v9, v12
	v_cndmask_b32_e64 v9, v12, v9, s[10:11]
	v_add_f32_e32 v12, 1.0, v18
	v_mul_f32_e32 v18, 0xbfb8aa3b, v11
	v_exp_f32_e32 v18, v18
	v_mul_f32_e32 v13, v13, v158
	v_rcp_f32_e32 v12, v12
	v_mul_f32_e32 v9, v13, v9
	v_mul_f32_e32 v13, v14, v158
	v_add_f32_e32 v14, 1.0, v18
	v_rcp_f32_e32 v14, v14
	v_mul_f32_e32 v12, v10, v12
	v_cndmask_b32_e64 v10, v12, v10, s[10:11]
	v_mul_f32_e32 v0, v0, v158
	v_mul_f32_e32 v10, v13, v10
	v_mul_f32_e32 v13, v11, v14
	v_mul_f32_e32 v14, 0xbfb8aa3b, v0
	v_exp_f32_e32 v14, v14
	v_mul_f32_e32 v12, v15, v158
	v_cndmask_b32_e64 v11, v13, v11, s[10:11]
	v_mul_f32_e32 v11, v12, v11
	v_add_f32_e32 v12, 1.0, v14
	v_rcp_f32_e32 v12, v12
	v_mul_f32_e32 v1, v1, v158
	v_mul_f32_e32 v13, 0xbfb8aa3b, v1
	v_exp_f32_e32 v13, v13
	v_mul_f32_e32 v12, v0, v12
	v_mul_f32_e32 v4, v4, v158
	v_cndmask_b32_e64 v0, v12, v0, s[10:11]
	v_mul_f32_e32 v12, v4, v0
	v_add_f32_e32 v0, 1.0, v13
	v_mul_f32_e32 v2, v2, v158
	v_rcp_f32_e32 v0, v0
	v_mul_f32_e32 v4, 0xbfb8aa3b, v2
	v_exp_f32_e32 v4, v4
	v_mul_f32_e32 v3, v3, v158
	v_mul_f32_e32 v0, v1, v0
	v_cndmask_b32_e64 v0, v0, v1, s[10:11]
	v_add_f32_e32 v1, 1.0, v4
	v_mul_f32_e32 v4, 0xbfb8aa3b, v3
	v_exp_f32_e32 v4, v4
	v_rcp_f32_e32 v1, v1
	v_mul_f32_e32 v5, v5, v158
	v_mul_f32_e32 v13, v5, v0
	v_add_f32_e32 v4, 1.0, v4
	v_rcp_f32_e32 v4, v4
	v_mul_f32_e32 v1, v2, v1
	v_mul_f32_e32 v0, v6, v158
	v_cndmask_b32_e64 v1, v1, v2, s[10:11]
	v_mul_f32_e32 v6, v0, v1
	v_mul_f32_e32 v1, v3, v4
	v_mul_f32_e32 v0, v7, v158
	v_cndmask_b32_e64 v1, v1, v3, s[10:11]
	v_mul_f32_e32 v3, v0, v1
	v_lshl_add_u64 v[4:5], v[16:17], 1, v[176:177]
	v_cvt_pk_bf16_f32 v0, v8, v9
	v_cvt_pk_bf16_f32 v1, v10, v11
	v_cvt_pk_bf16_f32 v2, v12, v13
	v_cvt_pk_bf16_f32 v3, v6, v3
	ds_write_b128 v184, v[0:3] offset:1024
	ds_read_b128 v[192:195], v185 offset:1024
	v_mov_b32_e32 v198, v4
	v_mov_b32_e32 v199, v5
	s_waitcnt lgkmcnt(2)
	global_store_dwordx4 v[196:197], v[188:191], off
	s_waitcnt lgkmcnt(0)
	global_store_dwordx4 v[198:199], v[192:195], off
	s_andn2_b64 vcc, exec, s[8:9]
	s_mov_b64 s[8:9], -1
	s_cbranch_vccnz .LBB0_1444
